# last workgroup: S5 table build uses wide loads/stores up front, phase-3 bias fold issues its 33 loads before the adds
# baseline (speedup 1.0000x reference)
; __global__ void __launch_bounds__(512, 2) mega(P p, int ph_lo, int ph_hi, unsigned ph_mask) {
;     ...
;         case 3: if (c == G - 1) { const int t = tid; const int kv = t >> 8, n = t & 255; float a = p.in[kv ? 25 : 22][n];
;                     for (int s = 0; s < 32; ++s) a += ((const float*)(ws + W_B1PART))[(kv * 32 + s) * 256 + n];
;                     ((float*)(ws + W_B1P))[kv * 256 + n] = a; }
.LBB0_409:
	s_mov_b64 s[16:17], 0
	v_writelane_b32 v254, s16, 49
	s_mov_b64 s[4:5], 0
	s_and_b64 vcc, exec, s[0:1]
	v_writelane_b32 v254, s17, 50
	s_cbranch_vccz .LBB0_485
	s_cmp_gt_i32 s64, 1
	s_mov_b64 s[0:1], -1
	s_cbranch_scc0 .LBB0_638
	s_cmp_gt_i32 s64, 2
	s_cbranch_scc0 .LBB0_581
	v_readlane_b32 s0, v250, 52
	v_readlane_b32 s1, v250, 53
	s_andn2_b64 vcc, exec, s[0:1]
	s_cbranch_vccnz .LBB0_414
	v_readlane_b32 s4, v251, 50
	v_readlane_b32 s8, v251, 54
	v_readlane_b32 s9, v251, 55
	v_readlane_b32 s10, v251, 56
	v_readlane_b32 s11, v251, 57
	v_readlane_b32 s12, v251, 58
	v_readlane_b32 s13, v251, 59
	v_readlane_b32 s14, v251, 60
	v_readlane_b32 s15, v251, 61
	v_readlane_b32 s16, v251, 62
	v_readlane_b32 s17, v251, 63
	v_readlane_b32 s18, v252, 0
	v_readlane_b32 s19, v252, 1
	v_readlane_b32 s8, v252, 2
	s_movk_i32 s0, 0x100
	v_readlane_b32 s7, v251, 53
	v_readlane_b32 s21, v252, 15
	v_cmp_gt_u32_e32 vcc, s0, v182
	v_readlane_b32 s6, v251, 52
	v_mov_b32_e32 v0, s7
	v_readlane_b32 s20, v252, 14
	v_mov_b32_e32 v1, s21
	v_and_b32_e32 v2, 0xff, v182
	v_cndmask_b32_e32 v1, v0, v1, vcc
	v_mov_b32_e32 v0, s6
	v_mov_b32_e32 v3, s20
	v_cndmask_b32_e32 v0, v0, v3, vcc
	v_lshlrev_b32_e32 v180, 2, v2
	v_lshl_add_u64 v[0:1], v[0:1], 0, v[180:181]
	global_load_dword v100, v[0:1], off
	v_lshlrev_b32_e32 v0, 5, v182
	s_movk_i32 s0, 0xe000
	v_and_or_b32 v0, v0, s0, v2
	v_readlane_b32 s0, v250, 54
	v_ashrrev_i32_e32 v1, 31, v0
	v_readlane_b32 s1, v250, 55
	s_movk_i32 s4, 0x1000
	v_ashrrev_i32_e32 v183, 31, v182
	v_lshl_add_u64 v[2:3], v[0:1], 2, s[0:1]
	global_load_dword v101, v[2:3], off
	v_or_b32_e32 v0, 0x1f00, v0
	v_readlane_b32 s5, v251, 51
	v_readlane_b32 s9, v252, 3
	v_readlane_b32 s10, v252, 4
	v_readlane_b32 s11, v252, 5
	v_readlane_b32 s12, v252, 6
	v_readlane_b32 s13, v252, 7
	v_readlane_b32 s14, v252, 8
	v_readlane_b32 s15, v252, 9
	v_readlane_b32 s16, v252, 10
	v_readlane_b32 s17, v252, 11
	v_readlane_b32 s18, v252, 12
	v_readlane_b32 s19, v252, 13
	v_readlane_b32 s22, v252, 16
	v_readlane_b32 s23, v252, 17
	global_load_dword v102, v[2:3], off offset:1024
	global_load_dword v103, v[2:3], off offset:2048
	global_load_dword v104, v[2:3], off offset:3072
	v_add_co_u32_e32 v4, vcc, s4, v2
	s_movk_i32 s4, 0x2000
	s_nop 0
	v_addc_co_u32_e32 v5, vcc, 0, v3, vcc
	v_add_co_u32_e32 v6, vcc, s4, v2
	s_movk_i32 s4, 0x3000
	s_nop 0
	v_addc_co_u32_e32 v7, vcc, 0, v3, vcc
	global_load_dword v105, v[6:7], off offset:-4096
	global_load_dword v106, v[4:5], off offset:1024
	global_load_dword v107, v[4:5], off offset:2048
	global_load_dword v108, v[4:5], off offset:3072
	global_load_dword v109, v[6:7], off
	global_load_dword v110, v[6:7], off offset:1024
	global_load_dword v111, v[6:7], off offset:2048
	global_load_dword v112, v[6:7], off offset:3072
	v_add_co_u32_e32 v4, vcc, s4, v2
	s_movk_i32 s4, 0x4000
	s_nop 0
	v_addc_co_u32_e32 v5, vcc, 0, v3, vcc
	v_add_co_u32_e32 v6, vcc, s4, v2
	s_movk_i32 s4, 0x5000
	s_nop 0
	v_addc_co_u32_e32 v7, vcc, 0, v3, vcc
	global_load_dword v113, v[6:7], off offset:-4096
	global_load_dword v114, v[4:5], off offset:1024
	global_load_dword v115, v[4:5], off offset:2048
	global_load_dword v116, v[4:5], off offset:3072
	global_load_dword v117, v[6:7], off
	global_load_dword v118, v[6:7], off offset:1024
	global_load_dword v119, v[6:7], off offset:2048
	global_load_dword v120, v[6:7], off offset:3072
	v_add_co_u32_e32 v4, vcc, s4, v2
	s_movk_i32 s4, 0x6000
	s_nop 0
	v_addc_co_u32_e32 v5, vcc, 0, v3, vcc
	v_add_co_u32_e32 v6, vcc, s4, v2
	s_movk_i32 s4, 0x7000
	s_nop 0
	v_addc_co_u32_e32 v7, vcc, 0, v3, vcc
	global_load_dword v121, v[6:7], off offset:-4096
	v_add_co_u32_e32 v2, vcc, s4, v2
	global_load_dword v122, v[4:5], off offset:1024
	s_nop 0
	v_addc_co_u32_e32 v3, vcc, 0, v3, vcc
	global_load_dword v123, v[4:5], off offset:2048
	global_load_dword v124, v[4:5], off offset:3072
	global_load_dword v125, v[6:7], off
	global_load_dword v126, v[6:7], off offset:1024
	global_load_dword v127, v[6:7], off offset:2048
	global_load_dword v128, v[6:7], off offset:3072
	global_load_dword v129, v[2:3], off
	global_load_dword v130, v[2:3], off offset:1024
	global_load_dword v131, v[2:3], off offset:2048
	v_ashrrev_i32_e32 v1, 31, v0
	v_lshl_add_u64 v[0:1], v[0:1], 2, s[0:1]
	global_load_dword v132, v[0:1], off
	s_waitcnt vmcnt(0)
	v_add_f32_e32 v140, v100, v101
	v_add_f32_e32 v141, v140, v102
	v_add_f32_e32 v140, v141, v103
	v_add_f32_e32 v141, v140, v104
	v_add_f32_e32 v140, v141, v105
	v_add_f32_e32 v141, v140, v106
	v_add_f32_e32 v140, v141, v107
	v_add_f32_e32 v141, v140, v108
	v_add_f32_e32 v140, v141, v109
	v_add_f32_e32 v141, v140, v110
	v_add_f32_e32 v140, v141, v111
	v_add_f32_e32 v141, v140, v112
	v_add_f32_e32 v140, v141, v113
	v_add_f32_e32 v141, v140, v114
	v_add_f32_e32 v140, v141, v115
	v_add_f32_e32 v141, v140, v116
	v_add_f32_e32 v140, v141, v117
	v_add_f32_e32 v141, v140, v118
	v_add_f32_e32 v140, v141, v119
	v_add_f32_e32 v141, v140, v120
	v_add_f32_e32 v140, v141, v121
	v_add_f32_e32 v141, v140, v122
	v_add_f32_e32 v140, v141, v123
	v_add_f32_e32 v141, v140, v124
	v_add_f32_e32 v140, v141, v125
	v_add_f32_e32 v141, v140, v126
	v_add_f32_e32 v140, v141, v127
	v_add_f32_e32 v141, v140, v128
	v_add_f32_e32 v140, v141, v129
	v_add_f32_e32 v141, v140, v130
	v_add_f32_e32 v140, v141, v131
	v_readlane_b32 s0, v250, 31
	v_readlane_b32 s1, v250, 32
	v_add_f32_e32 v141, v140, v132
	s_nop 0
	v_lshl_add_u64 v[0:1], v[182:183], 2, s[0:1]
	global_store_dword v[0:1], v141, off

; DI void prologue_phase(const int tid, LAS unsigned char* lds, const P& p, int G, int c) {
;     ...
;         for (int idx = tid; idx < 1024; idx += 512) { const int g = idx >> 6;
;             const float step = expf(p.in[5][g]), lr = p.in[3][idx], li = p.in[4][idx];
;             const float mag = expf(lr * step), are = mag * cosf(li * step), aim = mag * sinf(li * step);
;             const float den = lr * lr + li * li, nre = are - 1.f, nim = aim;
;             const float zre = (nre * lr + nim * li) / den, zim = (nim * lr - nre * li) / den;
;             abar[idx * 2] = are; abar[idx * 2 + 1] = aim;
;             for (int h = 0; h < 16; ++h) { const float br = p.in[6][idx * 16 + h], bi = p.in[7][idx * 16 + h]; bbar[idx * 32 + h] = zre * br - zim * bi; bbar[idx * 32 + 16 + h] = zre * bi + zim * br; } }
.LBB0_1629:
	s_or_b64 exec, exec, s[0:1]
	v_mul_f32_e32 v12, v12, v1
	v_mul_f32_e32 v15, 0x3fb8aa3b, v12
	v_fma_f32 v16, v12, s28, -v15
	v_rndne_f32_e32 v19, v15
	v_fmac_f32_e32 v16, 0x32a5705f, v12
	v_sub_f32_e32 v15, v15, v19
	v_add_f32_e32 v15, v15, v16
	v_cvt_i32_f32_e32 v16, v19
	v_exp_f32_e32 v15, v15
	v_cmp_ngt_f32_e32 vcc, s34, v12
	v_mov_b32_e32 v21, 0xbab64f3b
	s_brev_b32 s0, 1
	v_ldexp_f32 v15, v15, v16
	v_cndmask_b32_e32 v15, 0, v15, vcc
	v_cmp_nlt_f32_e32 vcc, s36, v12
	v_mul_f32_e32 v12, v14, v14
	v_mov_b32_e32 v16, 0x3c0881c4
	v_cndmask_b32_e32 v19, v237, v15, vcc
	v_fmamk_f32 v15, v12, 0xb94c1982, v16
	v_fmaak_f32 v15, v12, v15, 0xbe2aaa9d
	v_mul_f32_e32 v15, v12, v15
	v_fmac_f32_e32 v14, v14, v15
	v_fmamk_f32 v15, v12, 0x37d75334, v21
	v_fmaak_f32 v15, v12, v15, 0x3d2aabf7
	v_fmaak_f32 v15, v12, v15, 0xbf000004
	v_fma_f32 v12, v12, v15, 1.0
	v_and_b32_e32 v15, 1, v13
	v_cmp_eq_u32_e32 vcc, 0, v15
	v_lshlrev_b32_e32 v13, 30, v13
	v_mov_b32_e32 v15, 0x7fc00000
	v_cndmask_b32_e64 v12, -v14, v12, vcc
	v_bitop3_b32 v12, v13, v12, s0 bitop3:0x6c
	v_mul_f32_e32 v13, v18, v18
	v_fmamk_f32 v14, v13, 0xb94c1982, v16
	v_fmaak_f32 v14, v13, v14, 0xbe2aaa9d
	v_mul_f32_e32 v14, v13, v14
	v_fmac_f32_e32 v18, v18, v14
	v_fmamk_f32 v14, v13, 0x37d75334, v21
	v_fmaak_f32 v14, v13, v14, 0x3d2aabf7
	v_fmaak_f32 v14, v13, v14, 0xbf000004
	s_movk_i32 s0, 0x1f8
	v_fma_f32 v13, v13, v14, 1.0
	v_and_b32_e32 v14, 1, v17
	v_cmp_class_f32_e64 vcc, v3, s0
	v_cmp_eq_u32_e64 s[0:1], 0, v14
	v_lshlrev_b32_e32 v14, 30, v17
	v_and_b32_e32 v14, 0x80000000, v14
	v_xor_b32_e32 v3, v5, v3
	v_cndmask_b32_e64 v13, v13, v18, s[0:1]
	v_xor_b32_e32 v3, v3, v14
	v_xor_b32_e32 v3, v3, v13
	v_readlane_b32 s0, v251, 29
	v_cndmask_b32_e32 v20, v15, v12, vcc
	v_cndmask_b32_e32 v3, v15, v3, vcc
	v_ashrrev_i32_e32 v5, 31, v4
	v_readlane_b32 s1, v251, 30
	v_mul_f32_e32 v12, v19, v20
	v_mul_f32_e32 v13, v19, v3
	v_lshl_add_u64 v[14:15], v[4:5], 2, s[0:1]
	v_ashrrev_i32_e32 v3, 31, v2
	v_readlane_b32 s72, v253, 30
	global_store_dwordx2 v[14:15], v[12:13], off
	v_lshlrev_b64 v[14:15], 2, v[2:3]
	v_readlane_b32 s84, v253, 42
	v_readlane_b32 s85, v253, 43
	v_readlane_b32 s86, v253, 44
	v_readlane_b32 s87, v253, 45
	v_lshl_add_u64 v[16:17], s[84:85], 0, v[14:15]
	v_mul_f32_e32 v12, v11, v11
	v_lshl_add_u64 v[14:15], s[86:87], 0, v[14:15]
	global_load_dwordx4 v[44:47], v[14:15], off
	global_load_dwordx4 v[48:51], v[14:15], off offset:16
	global_load_dwordx4 v[52:55], v[14:15], off offset:32
	global_load_dwordx4 v[56:59], v[14:15], off offset:48
	global_load_dwordx4 v[60:63], v[16:17], off
	global_load_dwordx4 v[64:67], v[16:17], off offset:16
	global_load_dwordx4 v[68:71], v[16:17], off offset:32
	global_load_dwordx4 v[72:75], v[16:17], off offset:48
	v_fma_f32 v18, v19, v20, -1.0
	v_mul_f32_e32 v19, v11, v13
	v_fmac_f32_e32 v12, v1, v1
	v_mul_f32_e32 v11, v11, v18
	v_fmac_f32_e32 v19, v1, v18
	v_fma_f32 v1, v1, v13, -v11
	v_div_scale_f32 v11, s[0:1], v12, v12, v19
	v_div_scale_f32 v18, s[0:1], v12, v12, v1
	v_rcp_f32_e32 v20, v11
	v_rcp_f32_e32 v21, v18
	v_div_scale_f32 v13, vcc, v19, v12, v19
	v_fma_f32 v23, -v11, v20, 1.0
	v_fma_f32 v24, -v18, v21, 1.0
	v_fmac_f32_e32 v20, v23, v20
	v_div_scale_f32 v22, s[0:1], v1, v12, v1
	v_fmac_f32_e32 v21, v24, v21
	v_mul_f32_e32 v23, v13, v20
	v_mul_f32_e32 v24, v22, v21
	v_fma_f32 v25, -v11, v23, v13
	v_fma_f32 v26, -v18, v24, v22
	v_fmac_f32_e32 v23, v25, v20
	v_fmac_f32_e32 v24, v26, v21
	v_fma_f32 v11, -v11, v23, v13
	v_fma_f32 v13, -v18, v24, v22
	v_div_fmas_f32 v11, v11, v20, v23
	s_mov_b64 vcc, s[0:1]
	v_div_fmas_f32 v13, v13, v21, v24
	v_div_fixup_f32 v18, v13, v12, v1
	v_div_fixup_f32 v11, v11, v12, v19
	v_readlane_b32 s0, v251, 31
	v_readlane_b32 s1, v251, 32
	s_mov_b32 s4, 0x3fb8aa3b
	s_mov_b32 s5, 0xc2ce8ed0
	s_mov_b32 s6, 0x42b17218
	v_readlane_b32 s82, v253, 40
	v_readlane_b32 s83, v253, 41
	v_add_u32_e32 v2, 0x2000, v2
	v_add_u32_e32 v4, 0x400, v4
	v_readlane_b32 s73, v253, 31
	v_readlane_b32 s74, v253, 32
	v_readlane_b32 s75, v253, 33
	v_readlane_b32 s76, v253, 34
	v_readlane_b32 s77, v253, 35
	v_readlane_b32 s78, v253, 36
	v_readlane_b32 s79, v253, 37
	v_readlane_b32 s80, v253, 38
	v_readlane_b32 s81, v253, 39
	v_ashrrev_i32_e32 v1, 31, v0
	v_lshl_add_u64 v[12:13], v[0:1], 2, s[0:1]
	s_mov_b64 s[0:1], 0x800
	v_lshl_add_u64 v[6:7], v[6:7], 0, s[0:1]
	v_lshl_add_u64 v[8:9], v[8:9], 0, s[0:1]
	s_movk_i32 s0, 0x1ff
	v_cmp_lt_i32_e32 vcc, s0, v10
	v_add_u32_e32 v0, 0x4000, v0
	s_or_b64 s[10:11], vcc, s[10:11]
	s_waitcnt vmcnt(0)
	v_mul_f32_e32 v76, v44, v18
	v_mul_f32_e32 v92, v44, v11
	v_fma_f32 v76, v60, v11, -v76
	v_fmac_f32_e32 v92, v60, v18
	v_mul_f32_e32 v77, v45, v18
	v_mul_f32_e32 v93, v45, v11
	v_fma_f32 v77, v61, v11, -v77
	v_fmac_f32_e32 v93, v61, v18
	v_mul_f32_e32 v78, v46, v18
	v_mul_f32_e32 v94, v46, v11
	v_fma_f32 v78, v62, v11, -v78
	v_fmac_f32_e32 v94, v62, v18
	v_mul_f32_e32 v79, v47, v18
	v_mul_f32_e32 v95, v47, v11
	v_fma_f32 v79, v63, v11, -v79
	v_fmac_f32_e32 v95, v63, v18
	v_mul_f32_e32 v80, v48, v18
	v_mul_f32_e32 v96, v48, v11
	v_fma_f32 v80, v64, v11, -v80
	v_fmac_f32_e32 v96, v64, v18
	v_mul_f32_e32 v81, v49, v18
	v_mul_f32_e32 v97, v49, v11
	v_fma_f32 v81, v65, v11, -v81
	v_fmac_f32_e32 v97, v65, v18
	v_mul_f32_e32 v82, v50, v18
	v_mul_f32_e32 v98, v50, v11
	v_fma_f32 v82, v66, v11, -v82
	v_fmac_f32_e32 v98, v66, v18
	v_mul_f32_e32 v83, v51, v18
	v_mul_f32_e32 v99, v51, v11
	v_fma_f32 v83, v67, v11, -v83
	v_fmac_f32_e32 v99, v67, v18
	v_mul_f32_e32 v84, v52, v18
	v_mul_f32_e32 v100, v52, v11
	v_fma_f32 v84, v68, v11, -v84
	v_fmac_f32_e32 v100, v68, v18
	v_mul_f32_e32 v85, v53, v18
	v_mul_f32_e32 v101, v53, v11
	v_fma_f32 v85, v69, v11, -v85
	v_fmac_f32_e32 v101, v69, v18
	v_mul_f32_e32 v86, v54, v18
	v_mul_f32_e32 v102, v54, v11
	v_fma_f32 v86, v70, v11, -v86
	v_fmac_f32_e32 v102, v70, v18
	v_mul_f32_e32 v87, v55, v18
	v_mul_f32_e32 v103, v55, v11
	v_fma_f32 v87, v71, v11, -v87
	v_fmac_f32_e32 v103, v71, v18
	v_mul_f32_e32 v88, v56, v18
	v_mul_f32_e32 v104, v56, v11
	v_fma_f32 v88, v72, v11, -v88
	v_fmac_f32_e32 v104, v72, v18
	v_mul_f32_e32 v89, v57, v18
	v_mul_f32_e32 v105, v57, v11
	v_fma_f32 v89, v73, v11, -v89
	v_fmac_f32_e32 v105, v73, v18
	v_mul_f32_e32 v90, v58, v18
	v_mul_f32_e32 v106, v58, v11
	v_fma_f32 v90, v74, v11, -v90
	v_fmac_f32_e32 v106, v74, v18
	v_mul_f32_e32 v91, v59, v18
	v_mul_f32_e32 v107, v59, v11
	v_fma_f32 v91, v75, v11, -v91
	v_fmac_f32_e32 v107, v75, v18
	global_store_dwordx4 v[12:13], v[76:79], off
	global_store_dwordx4 v[12:13], v[80:83], off offset:16
	global_store_dwordx4 v[12:13], v[84:87], off offset:32
	global_store_dwordx4 v[12:13], v[88:91], off offset:48
	global_store_dwordx4 v[12:13], v[92:95], off offset:64
	global_store_dwordx4 v[12:13], v[96:99], off offset:80
	global_store_dwordx4 v[12:13], v[100:103], off offset:96
	global_store_dwordx4 v[12:13], v[104:107], off offset:112
	v_add_u32_e32 v5, 0x200, v10
	v_mov_b32_e32 v10, v5
	s_andn2_b64 exec, exec, s[10:11]
	s_cbranch_execz .LBB0_1638
